# attention: second half of the score bias-init packed adds moved into the gaps of the first QK MFMA chain
# speedup vs baseline: 1.0014x; 1.0014x over previous
.LBB0_572:
	s_add_i32 s9, s9, 3
	s_cmp_lt_u32 s83, 4
	s_cselect_b32 s8, s8, s9
	v_lshl_add_u32 v156, s8, 6, v151
	v_cvt_f32_i32_e32 v66, v156
	s_cmp_lt_i32 s8, s84
	v_fma_f32 v81, v117, v66, -v155
	v_add_f32_e32 v97, v149, v81
	v_pk_add_f32 v[66:67], v[190:191], v[80:81] op_sel:[0,1] op_sel_hi:[1,1]
	v_pk_add_f32 v[68:69], v[134:135], v[80:81] op_sel:[0,1] op_sel_hi:[1,1]
	v_pk_add_f32 v[70:71], v[136:137], v[80:81] op_sel:[0,1] op_sel_hi:[1,1]
	v_pk_add_f32 v[72:73], v[138:139], v[80:81] op_sel:[0,1] op_sel_hi:[1,1]
	v_pk_add_f32 v[74:75], v[140:141], v[80:81] op_sel:[0,1] op_sel_hi:[1,1]
	v_pk_add_f32 v[76:77], v[142:143], v[80:81] op_sel:[0,1] op_sel_hi:[1,1]
	v_pk_add_f32 v[78:79], v[144:145], v[80:81] op_sel:[0,1] op_sel_hi:[1,1]
	v_pk_add_f32 v[80:81], v[216:217], v[80:81] op_sel:[0,1] op_sel_hi:[1,1]
	s_waitcnt lgkmcnt(4)
	s_nop 1
	v_mfma_f32_32x32x16_bf16 v[66:81], v[192:195], v[98:101], v[66:81]
	v_pk_add_f32 v[82:83], v[190:191], v[96:97] op_sel:[0,1] op_sel_hi:[1,1]
	v_pk_add_f32 v[84:85], v[134:135], v[96:97] op_sel:[0,1] op_sel_hi:[1,1]
	v_mfma_f32_32x32x16_bf16 v[66:81], v[200:203], v[102:105], v[66:81]
	v_pk_add_f32 v[86:87], v[136:137], v[96:97] op_sel:[0,1] op_sel_hi:[1,1]
	v_pk_add_f32 v[88:89], v[138:139], v[96:97] op_sel:[0,1] op_sel_hi:[1,1]
	v_mfma_f32_32x32x16_bf16 v[66:81], v[208:211], v[106:109], v[66:81]
	v_pk_add_f32 v[90:91], v[140:141], v[96:97] op_sel:[0,1] op_sel_hi:[1,1]
	v_pk_add_f32 v[92:93], v[142:143], v[96:97] op_sel:[0,1] op_sel_hi:[1,1]
	v_mfma_f32_32x32x16_bf16 v[66:81], v[220:223], v[110:113], v[66:81]
	v_pk_add_f32 v[94:95], v[144:145], v[96:97] op_sel:[0,1] op_sel_hi:[1,1]
	v_pk_add_f32 v[96:97], v[216:217], v[96:97] op_sel:[0,1] op_sel_hi:[1,1]
	s_waitcnt lgkmcnt(0)
	s_nop 1
	v_mfma_f32_32x32x16_bf16 v[82:97], v[196:199], v[98:101], v[82:97]
	v_mfma_f32_32x32x16_bf16 v[82:97], v[204:207], v[102:105], v[82:97]
	v_mfma_f32_32x32x16_bf16 v[82:97], v[212:215], v[106:109], v[82:97]
	v_mfma_f32_32x32x16_bf16 v[82:97], v[228:231], v[110:113], v[82:97]
	s_cbranch_scc1 .LBB0_574
	s_movk_i32 s36, 0xffe6
	s_movk_i32 s64, 0xffe5
	s_movk_i32 s34, 0xffe7
	v_cmp_lt_i32_e64 s[62:63], s36, v156
	v_cmp_lt_i32_e64 s[64:65], s64, v156
	s_movk_i32 s30, 0xffe8
	v_cmp_lt_i32_e64 s[60:61], s34, v156
	s_and_b64 s[62:63], s[64:65], s[62:63]
	s_movk_i32 s28, 0xffed
	v_cmp_lt_i32_e64 s[58:59], s30, v156
	s_and_b64 s[60:61], s[62:63], s[60:61]
	s_movk_i32 s26, 0xffee
	v_cmp_lt_i32_e64 s[56:57], s28, v156
	s_and_b64 s[58:59], s[60:61], s[58:59]
	s_movk_i32 s24, 0xffef
	v_cmp_lt_i32_e64 s[54:55], s26, v156
	s_and_b64 s[56:57], s[58:59], s[56:57]
	v_cmp_lt_i32_e64 s[52:53], s24, v156
	s_and_b64 s[54:55], s[56:57], s[54:55]
	v_cmp_lt_i32_e64 s[50:51], -16, v156
	s_and_b64 s[52:53], s[54:55], s[52:53]
	v_cmp_lt_i32_e64 s[48:49], -11, v156
	s_and_b64 s[50:51], s[52:53], s[50:51]
	v_cmp_lt_i32_e64 s[46:47], -10, v156
	s_and_b64 s[48:49], s[50:51], s[48:49]
	v_cmp_lt_i32_e64 s[44:45], -9, v156
	s_and_b64 s[46:47], s[48:49], s[46:47]
	s_movk_i32 s10, 0xffe0
	v_cmp_lt_i32_e64 s[42:43], -8, v156
	s_and_b64 s[44:45], s[46:47], s[44:45]
	v_cmp_gt_i32_e64 s[8:9], 1, v156
	v_cmp_lt_i32_e32 vcc, s10, v156
	v_cmp_gt_i32_e64 s[10:11], 0, v156
	v_cmp_lt_i32_e64 s[40:41], -3, v156
	s_and_b64 s[42:43], s[44:45], s[42:43]
	s_or_b64 s[8:9], s[10:11], s[8:9]
	v_cmp_lt_i32_e64 s[38:39], -2, v156
	s_and_b64 s[40:41], s[42:43], s[40:41]
	v_cndmask_b32_e64 v157, v127, v67, s[10:11]
	v_cndmask_b32_e64 v158, v127, v66, s[8:9]
	s_and_b64 s[38:39], s[40:41], s[38:39]
	s_movk_i32 s36, 0xffc6
	v_cndmask_b32_e64 v66, v66, v158, s[38:39]
	v_cndmask_b32_e64 v68, v68, v127, s[38:39]
	v_cndmask_b32_e64 v67, v67, v157, s[38:39]
	s_movk_i32 s38, 0xffc5
	s_movk_i32 s34, 0xffc7
	v_cmp_lt_i32_e64 s[36:37], s36, v156
	v_cmp_lt_i32_e64 s[38:39], s38, v156
	s_movk_i32 s30, 0xffc8
	v_cmp_lt_i32_e64 s[34:35], s34, v156
	s_and_b64 s[36:37], s[38:39], s[36:37]
	s_movk_i32 s28, 0xffcd
	v_cmp_lt_i32_e64 s[30:31], s30, v156
	s_and_b64 s[34:35], s[36:37], s[34:35]
	s_movk_i32 s26, 0xffce
	v_cmp_lt_i32_e64 s[28:29], s28, v156
	s_and_b64 s[30:31], s[34:35], s[30:31]
	s_movk_i32 s24, 0xffcf
	v_cmp_lt_i32_e64 s[26:27], s26, v156
	s_and_b64 s[28:29], s[30:31], s[28:29]
	s_movk_i32 s22, 0xffd0
	v_cmp_lt_i32_e64 s[24:25], s24, v156
	s_and_b64 s[26:27], s[28:29], s[26:27]
	s_movk_i32 s20, 0xffd5
	v_cmp_lt_i32_e64 s[22:23], s22, v156
	s_and_b64 s[24:25], s[26:27], s[24:25]
	s_movk_i32 s18, 0xffd6
	v_cmp_lt_i32_e64 s[20:21], s20, v156
	s_and_b64 s[22:23], s[24:25], s[22:23]
	s_movk_i32 s16, 0xffd7
	v_cmp_lt_i32_e64 s[18:19], s18, v156
	s_and_b64 s[20:21], s[22:23], s[20:21]
	s_movk_i32 s14, 0xffd8
	v_cmp_lt_i32_e64 s[16:17], s16, v156
	s_and_b64 s[18:19], s[20:21], s[18:19]
	s_movk_i32 s12, 0xffdd
	v_cmp_lt_i32_e64 s[14:15], s14, v156
	s_and_b64 s[16:17], s[18:19], s[16:17]
	s_movk_i32 s10, 0xffde
	v_cmp_lt_i32_e64 s[12:13], s12, v156
	s_and_b64 s[14:15], s[16:17], s[14:15]
	s_movk_i32 s8, 0xffdf
	v_cmp_lt_i32_e64 s[10:11], s10, v156
	s_and_b64 s[12:13], s[14:15], s[12:13]
	v_cmp_lt_i32_e64 s[8:9], s8, v156
	s_and_b64 s[10:11], s[12:13], s[10:11]
	s_and_b64 s[8:9], s[10:11], s[8:9]
	s_and_b64 vcc, s[8:9], vcc
	v_cndmask_b32_e64 v81, v81, v127, s[64:65]
	v_cndmask_b32_e64 v80, v80, v127, s[62:63]
	v_cndmask_b32_e64 v79, v79, v127, s[60:61]
	v_cndmask_b32_e64 v78, v78, v127, s[58:59]
	v_cndmask_b32_e64 v77, v77, v127, s[56:57]
	v_cndmask_b32_e64 v76, v76, v127, s[54:55]
	v_cndmask_b32_e64 v75, v75, v127, s[52:53]
	v_cndmask_b32_e64 v74, v74, v127, s[50:51]
	v_cndmask_b32_e64 v73, v73, v127, s[48:49]
	v_cndmask_b32_e64 v72, v72, v127, s[46:47]
	v_cndmask_b32_e64 v71, v71, v127, s[44:45]
	v_cndmask_b32_e64 v70, v70, v127, s[42:43]
	v_cndmask_b32_e64 v69, v69, v127, s[40:41]
	v_cndmask_b32_e64 v97, v97, v127, s[38:39]
	v_cndmask_b32_e64 v96, v96, v127, s[36:37]
	v_cndmask_b32_e64 v95, v95, v127, s[34:35]
	v_cndmask_b32_e64 v94, v94, v127, s[30:31]
	v_cndmask_b32_e64 v93, v93, v127, s[28:29]
	v_cndmask_b32_e64 v92, v92, v127, s[26:27]
	v_cndmask_b32_e64 v91, v91, v127, s[24:25]
	v_cndmask_b32_e64 v90, v90, v127, s[22:23]
	v_cndmask_b32_e64 v89, v89, v127, s[20:21]
	v_cndmask_b32_e64 v88, v88, v127, s[18:19]
	v_cndmask_b32_e64 v87, v87, v127, s[16:17]
	v_cndmask_b32_e64 v86, v86, v127, s[14:15]
	v_cndmask_b32_e64 v85, v85, v127, s[12:13]
	v_cndmask_b32_e64 v84, v84, v127, s[10:11]
	v_cndmask_b32_e64 v83, v83, v127, s[8:9]
	v_cndmask_b32_e32 v82, v82, v127, vcc
